# combination of the individually within-noise edits on top of the prologue hoist: P1 per-unit drains gated, v^T writer remap, ticket wait deferred, normaliser-row hoist
# baseline (speedup 1.0000x reference)
.LBB0_92:
	s_ashr_i32 s11, s10, 31
	v_cmp_lt_i64_e32 vcc, s[12:13], v[162:163]
	s_lshl_b64 s[12:13], s[10:11], 19
	v_readlane_b32 s18, v254, 38
	v_readlane_b32 s19, v254, 39
	s_add_u32 s12, s18, s12
	s_addc_u32 s13, s19, s13
	s_and_b64 s[20:21], vcc, exec
	s_cselect_b32 s11, s13, s5
	s_cselect_b32 s20, s12, s4
	s_ashr_i32 s9, s8, 31
	s_lshl_b64 s[22:23], s[8:9], 19
	s_add_u32 s30, s25, s22
	s_addc_u32 s31, s70, s23
	s_and_b64 s[22:23], vcc, exec
	s_cselect_b32 s9, s31, s35
	s_cselect_b32 s21, s30, s34
	s_add_u32 s4, s4, 0x40080
	s_addc_u32 s5, s5, 0
	s_add_u32 s22, s34, 0x100
	v_mov_b32_e32 v2, 0
	s_addc_u32 s23, s35, 0
	s_mov_b32 s36, -2
	v_mov_b32_e32 v3, v2
	v_mov_b32_e32 v4, v2
	v_mov_b32_e32 v5, v2
	v_mov_b32_e32 v6, v2
	v_mov_b32_e32 v7, v2
	v_mov_b32_e32 v8, v2
	v_mov_b32_e32 v9, v2
	v_mov_b32_e32 v18, v2
	v_mov_b32_e32 v19, v2
	v_mov_b32_e32 v20, v2
	v_mov_b32_e32 v21, v2
	v_mov_b32_e32 v22, v2
	v_mov_b32_e32 v23, v2
	v_mov_b32_e32 v24, v2
	v_mov_b32_e32 v25, v2
	v_mov_b32_e32 v34, v2
	v_mov_b32_e32 v35, v2
	v_mov_b32_e32 v36, v2
	v_mov_b32_e32 v37, v2
	v_mov_b32_e32 v38, v2
	v_mov_b32_e32 v39, v2
	v_mov_b32_e32 v40, v2
	v_mov_b32_e32 v41, v2
	v_mov_b32_e32 v50, v2
	v_mov_b32_e32 v51, v2
	v_mov_b32_e32 v52, v2
	v_mov_b32_e32 v53, v2
	v_mov_b32_e32 v54, v2
	v_mov_b32_e32 v55, v2
	v_mov_b32_e32 v56, v2
	v_mov_b32_e32 v57, v2
	v_mov_b32_e32 v10, v2
	v_mov_b32_e32 v11, v2
	v_mov_b32_e32 v12, v2
	v_mov_b32_e32 v13, v2
	v_mov_b32_e32 v14, v2
	v_mov_b32_e32 v15, v2
	v_mov_b32_e32 v16, v2
	v_mov_b32_e32 v17, v2
	v_mov_b32_e32 v26, v2
	v_mov_b32_e32 v27, v2
	v_mov_b32_e32 v28, v2
	v_mov_b32_e32 v29, v2
	v_mov_b32_e32 v30, v2
	v_mov_b32_e32 v31, v2
	v_mov_b32_e32 v32, v2
	v_mov_b32_e32 v33, v2
	v_mov_b32_e32 v42, v2
	v_mov_b32_e32 v43, v2
	v_mov_b32_e32 v44, v2
	v_mov_b32_e32 v45, v2
	v_mov_b32_e32 v46, v2
	v_mov_b32_e32 v47, v2
	v_mov_b32_e32 v48, v2
	v_mov_b32_e32 v49, v2
	v_mov_b32_e32 v58, v2
	v_mov_b32_e32 v59, v2
	v_mov_b32_e32 v60, v2
	v_mov_b32_e32 v61, v2
	v_mov_b32_e32 v62, v2
	v_mov_b32_e32 v63, v2
	v_mov_b32_e32 v64, v2
	v_mov_b32_e32 v65, v2
	v_mov_b32_e32 v66, v2
	v_mov_b32_e32 v67, v2
	v_mov_b32_e32 v68, v2
	v_mov_b32_e32 v69, v2
	v_mov_b32_e32 v70, v2
	v_mov_b32_e32 v71, v2
	v_mov_b32_e32 v72, v2
	v_mov_b32_e32 v73, v2
	v_mov_b32_e32 v98, v2
	v_mov_b32_e32 v99, v2
	v_mov_b32_e32 v100, v2
	v_mov_b32_e32 v101, v2
	v_mov_b32_e32 v102, v2
	v_mov_b32_e32 v103, v2
	v_mov_b32_e32 v104, v2
	v_mov_b32_e32 v105, v2
	v_mov_b32_e32 v114, v2
	v_mov_b32_e32 v115, v2
	v_mov_b32_e32 v116, v2
	v_mov_b32_e32 v117, v2
	v_mov_b32_e32 v118, v2
	v_mov_b32_e32 v119, v2
	v_mov_b32_e32 v120, v2
	v_mov_b32_e32 v121, v2
	v_mov_b32_e32 v130, v2
	v_mov_b32_e32 v131, v2
	v_mov_b32_e32 v132, v2
	v_mov_b32_e32 v133, v2
	v_mov_b32_e32 v134, v2
	v_mov_b32_e32 v135, v2
	v_mov_b32_e32 v136, v2
	v_mov_b32_e32 v137, v2
	v_mov_b32_e32 v90, v2
	v_mov_b32_e32 v91, v2
	v_mov_b32_e32 v92, v2
	v_mov_b32_e32 v93, v2
	v_mov_b32_e32 v94, v2
	v_mov_b32_e32 v95, v2
	v_mov_b32_e32 v96, v2
	v_mov_b32_e32 v97, v2
	v_mov_b32_e32 v106, v2
	v_mov_b32_e32 v107, v2
	v_mov_b32_e32 v108, v2
	v_mov_b32_e32 v109, v2
	v_mov_b32_e32 v110, v2
	v_mov_b32_e32 v111, v2
	v_mov_b32_e32 v112, v2
	v_mov_b32_e32 v113, v2
	v_mov_b32_e32 v122, v2
	v_mov_b32_e32 v123, v2
	v_mov_b32_e32 v124, v2
	v_mov_b32_e32 v125, v2
	v_mov_b32_e32 v126, v2
	v_mov_b32_e32 v127, v2
	v_mov_b32_e32 v128, v2
	v_mov_b32_e32 v129, v2
	v_mov_b32_e32 v138, v2
	v_mov_b32_e32 v139, v2
	v_mov_b32_e32 v140, v2
	v_mov_b32_e32 v141, v2
	v_mov_b32_e32 v142, v2
	v_mov_b32_e32 v143, v2
	v_mov_b32_e32 v144, v2
	v_mov_b32_e32 v145, v2

.LBB0_106:
	s_and_b64 vcc, exec, s[4:5]
	s_cbranch_vccnz .Lz_nobias
	s_waitcnt vmcnt(0)
.Lz_nobias:
	v_pk_add_f32 v[144:145], v[144:145], v[88:89]
	v_pk_add_f32 v[142:143], v[142:143], v[86:87]
	v_pk_add_f32 v[166:167], v[140:141], v[84:85]
	s_and_b64 vcc, exec, s[4:5]
	v_pk_add_f32 v[168:169], v[138:139], v[82:83]
	s_cbranch_vccnz .LBB0_108
	v_mul_f32_e32 v138, 0xbfb8aa3b, v142
	v_exp_f32_e32 v138, v138
	v_mul_f32_e32 v139, 0xbfb8aa3b, v168
	v_exp_f32_e32 v139, v139
	v_mul_f32_e32 v140, 0xbfb8aa3b, v169
	v_add_f32_e32 v138, 1.0, v138
	v_rcp_f32_e32 v142, v138
	v_mul_f32_e32 v138, 0xbfb8aa3b, v143
	v_exp_f32_e32 v138, v138
	v_exp_f32_e32 v140, v140
	v_add_f32_e32 v139, 1.0, v139
	v_rcp_f32_e32 v168, v139
	v_add_f32_e32 v138, 1.0, v138
	v_mul_f32_e32 v139, 0xbfb8aa3b, v144
	v_rcp_f32_e32 v143, v138
	v_add_f32_e32 v138, 1.0, v140
	v_exp_f32_e32 v139, v139
	v_mul_f32_e32 v140, 0xbfb8aa3b, v166
	v_exp_f32_e32 v140, v140
	v_rcp_f32_e32 v169, v138
	v_add_f32_e32 v138, 1.0, v139
	v_mul_f32_e32 v139, 0xbfb8aa3b, v145
	v_rcp_f32_e32 v144, v138
	v_add_f32_e32 v138, 1.0, v140
	v_exp_f32_e32 v139, v139
	v_mul_f32_e32 v140, 0xbfb8aa3b, v167
	v_exp_f32_e32 v140, v140
	v_rcp_f32_e32 v166, v138
	v_add_f32_e32 v138, 1.0, v139
	v_rcp_f32_e32 v145, v138
	v_add_f32_e32 v138, 1.0, v140
	v_rcp_f32_e32 v167, v138
